# scan loop head: step 2's kd/ka/r reads moved from the post-barrier burst into step 0's DPP gaps
# baseline (speedup 1.0000x reference)
.LBB0_1050:
	ds_read_b128 v[14:17], v0 offset:20480
	ds_read_b128 v[10:13], v0 offset:20496
	ds_read_b128 v[6:9], v0 offset:20512
	ds_read_b128 v[2:5], v0 offset:20528
	ds_read_b128 v[54:57], v89 offset:16384
	ds_read_b128 v[26:29], v89 offset:16640
	ds_read_b128 v[78:81], v89 offset:4096
	ds_read_b128 v[58:61], v89 offset:4352
	v_pk_mul_f32 v[66:67], v[74:75], v[108:109]
	s_waitcnt lgkmcnt(1)
	v_pk_mul_f32 v[78:79], v[14:15], v[78:79] op_sel_hi:[0,1]
	v_pk_fma_f32 v[66:67], v[76:77], v[110:111], v[66:67]
	v_pk_mul_f32 v[80:81], v[14:15], v[80:81] op_sel_hi:[0,1]
	v_add_f32_e32 v66, v66, v67
	v_pk_fma_f32 v[62:63], v[74:75], v[100:101], v[78:79]
	v_pk_fma_f32 v[64:65], v[76:77], v[102:103], v[80:81]
	v_add_f32_dpp v66, v66, v66 quad_perm:[1,0,3,2] row_mask:0xf bank_mask:0xf bound_ctrl:1
	ds_read_b128 v[30:33], v89 offset:4608
	v_mov_b32_e32 v0, v17
	v_mov_b32_e32 v82, v13
	v_add_f32_dpp v66, v66, v66 quad_perm:[2,3,0,1] row_mask:0xf bank_mask:0xf bound_ctrl:1
	ds_read_b128 v[22:25], v90 offset:8704
	v_mov_b32_e32 v84, v9
	v_mov_b32_e32 v86, v5
	v_add_f32_dpp v66, v66, v66 row_half_mirror row_mask:0xf bank_mask:0xf bound_ctrl:1
	ds_read_b128 v[18:21], v89 offset:16896
	s_add_i32 s26, s26, 1
	s_nop 0
	v_add_f32_dpp v66, v66, v66 row_ror:8 row_mask:0xf bank_mask:0xf bound_ctrl:1
	v_pk_fma_f32 v[62:63], v[120:121], v[66:67], v[62:63] op_sel_hi:[1,0,1] neg_lo:[1,0,0] neg_hi:[1,0,0]
	v_pk_fma_f32 v[64:65], v[122:123], v[66:67], v[64:65] op_sel_hi:[1,0,1] neg_lo:[1,0,0] neg_hi:[1,0,0]
	v_pk_mul_f32 v[50:51], v[112:113], v[62:63]
	v_pk_mul_f32 v[46:47], v[104:105], v[62:63]
	v_pk_fma_f32 v[50:51], v[114:115], v[64:65], v[50:51]
	s_waitcnt lgkmcnt(3)
	v_pk_fma_f32 v[66:67], v[14:15], v[58:59], v[46:47] op_sel:[1,0,0]
	v_add_f32_e32 v47, v50, v51
	v_pk_mul_f32 v[48:49], v[106:107], v[64:65]
	v_pk_mul_f32 v[56:57], v[56:57], v[64:65]
	v_add_f32_dpp v68, v47, v47 quad_perm:[1,0,3,2] row_mask:0xf bank_mask:0xf bound_ctrl:1
	v_pk_fma_f32 v[14:15], v[14:15], v[60:61], v[48:49] op_sel:[1,0,0]
	v_pk_fma_f32 v[54:55], v[54:55], v[62:63], v[56:57]
	v_add_f32_dpp v68, v68, v68 quad_perm:[2,3,0,1] row_mask:0xf bank_mask:0xf bound_ctrl:1
	v_add_f32_e32 v92, v54, v55
	s_nop 0
	v_add_f32_dpp v68, v68, v68 row_half_mirror row_mask:0xf bank_mask:0xf bound_ctrl:1
	ds_read_b128 v[46:49], v90 offset:768
	ds_read_b128 v[50:53], v89 offset:4864
	ds_read_b128 v[54:57], v90 offset:4864
	ds_read_b128 v[58:61], v90 offset:8960
	ds_read_b128 v[62:65], v89 offset:17152
	v_add_f32_dpp v68, v68, v68 row_ror:8 row_mask:0xf bank_mask:0xf bound_ctrl:1
	v_pk_fma_f32 v[42:43], v[128:129], v[68:69], v[66:67] op_sel_hi:[1,0,1] neg_lo:[1,0,0] neg_hi:[1,0,0]
	v_pk_fma_f32 v[14:15], v[130:131], v[68:69], v[14:15] op_sel_hi:[1,0,1] neg_lo:[1,0,0] neg_hi:[1,0,0]
	v_pk_mul_f32 v[38:39], v[124:125], v[42:43]
	v_pk_mul_f32 v[28:29], v[28:29], v[14:15]
	v_pk_mul_f32 v[36:37], v[118:119], v[14:15]
	v_pk_fma_f32 v[14:15], v[126:127], v[14:15], v[38:39]
	v_pk_mul_f32 v[34:35], v[116:117], v[42:43]
	v_add_f32_e32 v14, v14, v15
	v_pk_fma_f32 v[26:27], v[26:27], v[42:43], v[28:29]
	s_waitcnt lgkmcnt(7)
	v_pk_fma_f32 v[42:43], v[16:17], v[30:31], v[34:35] op_sel_hi:[0,1,1]
	v_add_f32_dpp v66, v14, v14 quad_perm:[1,0,3,2] row_mask:0xf bank_mask:0xf bound_ctrl:1
	v_pk_fma_f32 v[44:45], v[16:17], v[32:33], v[36:37] op_sel_hi:[0,1,1]
	v_add_f32_e32 v93, v26, v27
	v_add_f32_dpp v66, v66, v66 quad_perm:[2,3,0,1] row_mask:0xf bank_mask:0xf bound_ctrl:1
	ds_read_b128 v[14:17], v90 offset:1024
	ds_read_b128 v[26:29], v89 offset:5120
	ds_read_b128 v[30:33], v90 offset:5120
	ds_read_b128 v[34:37], v90 offset:9216
	ds_read_b128 v[38:41], v89 offset:17408
	v_add_f32_dpp v66, v66, v66 row_half_mirror row_mask:0xf bank_mask:0xf bound_ctrl:1
	s_nop 1
	v_add_f32_dpp v66, v66, v66 row_ror:8 row_mask:0xf bank_mask:0xf bound_ctrl:1
	s_waitcnt lgkmcnt(11)
	v_pk_fma_f32 v[22:23], v[22:23], v[66:67], v[42:43] op_sel_hi:[1,0,1] neg_lo:[1,0,0] neg_hi:[1,0,0]
	v_pk_fma_f32 v[24:25], v[24:25], v[66:67], v[44:45] op_sel_hi:[1,0,1] neg_lo:[1,0,0] neg_hi:[1,0,0]
	s_waitcnt lgkmcnt(7)
	v_pk_mul_f32 v[42:43], v[54:55], v[22:23]
	v_pk_mul_f32 v[20:21], v[20:21], v[24:25]
	v_pk_mul_f32 v[44:45], v[46:47], v[22:23]
	v_pk_mul_f32 v[46:47], v[48:49], v[24:25]
	v_pk_fma_f32 v[18:19], v[18:19], v[22:23], v[20:21]
	v_pk_fma_f32 v[20:21], v[56:57], v[24:25], v[42:43]
	v_pk_fma_f32 v[54:55], v[0:1], v[50:51], v[44:45] op_sel_hi:[0,1,1]
	v_pk_fma_f32 v[56:57], v[0:1], v[52:53], v[46:47] op_sel_hi:[0,1,1]
	v_add_f32_e32 v94, v18, v19
	v_add_f32_e32 v18, v20, v21
	s_nop 0
	s_nop 0
	v_add_f32_dpp v0, v18, v18 quad_perm:[1,0,3,2] row_mask:0xf bank_mask:0xf bound_ctrl:1
	ds_read_b128 v[18:21], v90 offset:1280
	ds_read_b128 v[22:25], v89 offset:5376
	v_add_f32_dpp v0, v0, v0 quad_perm:[2,3,0,1] row_mask:0xf bank_mask:0xf bound_ctrl:1
	ds_read_b128 v[42:45], v90 offset:5376
	ds_read_b128 v[46:49], v90 offset:9472
	v_add_f32_dpp v0, v0, v0 row_half_mirror row_mask:0xf bank_mask:0xf bound_ctrl:1
	ds_read_b128 v[50:53], v89 offset:17664
	s_nop 0
	v_add_f32_dpp v0, v0, v0 row_ror:8 row_mask:0xf bank_mask:0xf bound_ctrl:1
	s_waitcnt lgkmcnt(11)
	v_pk_fma_f32 v[54:55], v[58:59], v[0:1], v[54:55] op_sel_hi:[1,0,1] neg_lo:[1,0,0] neg_hi:[1,0,0]
	v_pk_fma_f32 v[56:57], v[60:61], v[0:1], v[56:57] op_sel_hi:[1,0,1] neg_lo:[1,0,0] neg_hi:[1,0,0]
	s_waitcnt lgkmcnt(7)
	v_pk_mul_f32 v[30:31], v[30:31], v[54:55]
	v_pk_mul_f32 v[58:59], v[64:65], v[56:57]
	v_pk_mul_f32 v[14:15], v[14:15], v[54:55]
	v_pk_fma_f32 v[54:55], v[62:63], v[54:55], v[58:59]
	v_pk_fma_f32 v[30:31], v[32:33], v[56:57], v[30:31]
	v_pk_fma_f32 v[62:63], v[10:11], v[26:27], v[14:15] op_sel_hi:[0,1,1]
	v_add_f32_e32 v95, v54, v55
	v_add_f32_e32 v14, v30, v31
	ds_write_b128 v91, v[92:95] offset:43008
	v_pk_mul_f32 v[16:17], v[16:17], v[56:57]
	v_add_f32_dpp v0, v14, v14 quad_perm:[1,0,3,2] row_mask:0xf bank_mask:0xf bound_ctrl:1
	v_pk_fma_f32 v[64:65], v[10:11], v[28:29], v[16:17] op_sel_hi:[0,1,1]
	ds_read_b128 v[14:17], v90 offset:1536
	v_add_f32_dpp v0, v0, v0 quad_perm:[2,3,0,1] row_mask:0xf bank_mask:0xf bound_ctrl:1
	ds_read_b128 v[26:29], v89 offset:5632
	ds_read_b128 v[30:33], v90 offset:5632
	v_add_f32_dpp v0, v0, v0 row_half_mirror row_mask:0xf bank_mask:0xf bound_ctrl:1
	ds_read_b128 v[54:57], v90 offset:9728
	ds_read_b128 v[58:61], v89 offset:17920
	v_add_f32_dpp v0, v0, v0 row_ror:8 row_mask:0xf bank_mask:0xf bound_ctrl:1
	s_waitcnt lgkmcnt(12)
	v_pk_fma_f32 v[34:35], v[34:35], v[0:1], v[62:63] op_sel_hi:[1,0,1] neg_lo:[1,0,0] neg_hi:[1,0,0]
	v_pk_fma_f32 v[36:37], v[36:37], v[0:1], v[64:65] op_sel_hi:[1,0,1] neg_lo:[1,0,0] neg_hi:[1,0,0]
	s_waitcnt lgkmcnt(8)
	v_pk_mul_f32 v[42:43], v[42:43], v[34:35]
	v_pk_mul_f32 v[40:41], v[40:41], v[36:37]
	v_pk_mul_f32 v[18:19], v[18:19], v[34:35]
	v_pk_mul_f32 v[20:21], v[20:21], v[36:37]
	v_pk_fma_f32 v[34:35], v[38:39], v[34:35], v[40:41]
	v_pk_fma_f32 v[36:37], v[44:45], v[36:37], v[42:43]
	v_pk_fma_f32 v[62:63], v[10:11], v[22:23], v[18:19] op_sel:[1,0,0]
	v_add_f32_e32 v18, v36, v37
	v_add_f32_e32 v96, v34, v35
	v_pk_fma_f32 v[10:11], v[10:11], v[24:25], v[20:21] op_sel:[1,0,0]
	v_add_f32_dpp v0, v18, v18 quad_perm:[1,0,3,2] row_mask:0xf bank_mask:0xf bound_ctrl:1
	ds_read_b128 v[18:21], v90 offset:1792
	ds_read_b128 v[22:25], v89 offset:5888
	v_add_f32_dpp v0, v0, v0 quad_perm:[2,3,0,1] row_mask:0xf bank_mask:0xf bound_ctrl:1
	ds_read_b128 v[34:37], v90 offset:5888
	ds_read_b128 v[38:41], v90 offset:9984
	v_add_f32_dpp v0, v0, v0 row_half_mirror row_mask:0xf bank_mask:0xf bound_ctrl:1
	ds_read_b128 v[42:45], v89 offset:18176
	s_nop 0
	v_add_f32_dpp v0, v0, v0 row_ror:8 row_mask:0xf bank_mask:0xf bound_ctrl:1
	s_waitcnt lgkmcnt(12)
	v_pk_fma_f32 v[46:47], v[46:47], v[0:1], v[62:63] op_sel_hi:[1,0,1] neg_lo:[1,0,0] neg_hi:[1,0,0]
	v_pk_fma_f32 v[10:11], v[48:49], v[0:1], v[10:11] op_sel_hi:[1,0,1] neg_lo:[1,0,0] neg_hi:[1,0,0]
	s_waitcnt lgkmcnt(7)
	v_pk_mul_f32 v[30:31], v[30:31], v[46:47]
	v_pk_mul_f32 v[48:49], v[52:53], v[10:11]
	v_pk_mul_f32 v[14:15], v[14:15], v[46:47]
	v_pk_mul_f32 v[16:17], v[16:17], v[10:11]
	v_pk_fma_f32 v[46:47], v[50:51], v[46:47], v[48:49]
	v_pk_fma_f32 v[10:11], v[32:33], v[10:11], v[30:31]
	v_add_f32_e32 v10, v10, v11
	v_add_f32_e32 v97, v46, v47
	v_pk_fma_f32 v[50:51], v[12:13], v[26:27], v[14:15] op_sel_hi:[0,1,1]
	v_add_f32_dpp v0, v10, v10 quad_perm:[1,0,3,2] row_mask:0xf bank_mask:0xf bound_ctrl:1
	v_pk_fma_f32 v[52:53], v[12:13], v[28:29], v[16:17] op_sel_hi:[0,1,1]
	ds_read_b128 v[10:13], v90 offset:2048
	v_add_f32_dpp v0, v0, v0 quad_perm:[2,3,0,1] row_mask:0xf bank_mask:0xf bound_ctrl:1
	ds_read_b128 v[14:17], v89 offset:6144
	ds_read_b128 v[26:29], v90 offset:6144
	v_add_f32_dpp v0, v0, v0 row_half_mirror row_mask:0xf bank_mask:0xf bound_ctrl:1
	ds_read_b128 v[30:33], v90 offset:10240
	ds_read_b128 v[46:49], v89 offset:18432
	v_add_f32_dpp v0, v0, v0 row_ror:8 row_mask:0xf bank_mask:0xf bound_ctrl:1
	s_waitcnt lgkmcnt(11)
	v_pk_fma_f32 v[50:51], v[54:55], v[0:1], v[50:51] op_sel_hi:[1,0,1] neg_lo:[1,0,0] neg_hi:[1,0,0]
	v_pk_fma_f32 v[52:53], v[56:57], v[0:1], v[52:53] op_sel_hi:[1,0,1] neg_lo:[1,0,0] neg_hi:[1,0,0]
	s_waitcnt lgkmcnt(7)
	v_pk_mul_f32 v[34:35], v[34:35], v[50:51]
	v_pk_mul_f32 v[54:55], v[60:61], v[52:53]
	v_pk_mul_f32 v[18:19], v[18:19], v[50:51]
	v_pk_fma_f32 v[50:51], v[58:59], v[50:51], v[54:55]
	v_pk_fma_f32 v[34:35], v[36:37], v[52:53], v[34:35]
	v_pk_fma_f32 v[58:59], v[82:83], v[22:23], v[18:19] op_sel_hi:[0,1,1]
	v_add_f32_e32 v18, v34, v35
	v_add_f32_e32 v98, v50, v51
	v_pk_mul_f32 v[20:21], v[20:21], v[52:53]
	v_add_f32_dpp v0, v18, v18 quad_perm:[1,0,3,2] row_mask:0xf bank_mask:0xf bound_ctrl:1
	v_pk_fma_f32 v[60:61], v[82:83], v[24:25], v[20:21] op_sel_hi:[0,1,1]
	ds_read_b128 v[18:21], v90 offset:2304
	v_add_f32_dpp v0, v0, v0 quad_perm:[2,3,0,1] row_mask:0xf bank_mask:0xf bound_ctrl:1
	ds_read_b128 v[22:25], v89 offset:6400
	ds_read_b128 v[34:37], v90 offset:6400
	v_add_f32_dpp v0, v0, v0 row_half_mirror row_mask:0xf bank_mask:0xf bound_ctrl:1
	ds_read_b128 v[50:53], v90 offset:10496
	ds_read_b128 v[54:57], v89 offset:18688
	v_add_f32_dpp v0, v0, v0 row_ror:8 row_mask:0xf bank_mask:0xf bound_ctrl:1
	s_waitcnt lgkmcnt(11)
	v_pk_fma_f32 v[38:39], v[38:39], v[0:1], v[58:59] op_sel_hi:[1,0,1] neg_lo:[1,0,0] neg_hi:[1,0,0]
	v_pk_fma_f32 v[40:41], v[40:41], v[0:1], v[60:61] op_sel_hi:[1,0,1] neg_lo:[1,0,0] neg_hi:[1,0,0]
	s_waitcnt lgkmcnt(7)
	v_pk_mul_f32 v[26:27], v[26:27], v[38:39]
	v_pk_mul_f32 v[44:45], v[44:45], v[40:41]
	v_pk_mul_f32 v[10:11], v[10:11], v[38:39]
	v_pk_fma_f32 v[38:39], v[42:43], v[38:39], v[44:45]
	v_pk_fma_f32 v[26:27], v[28:29], v[40:41], v[26:27]
	v_pk_fma_f32 v[58:59], v[6:7], v[14:15], v[10:11] op_sel_hi:[0,1,1]
	v_add_f32_e32 v99, v38, v39
	v_add_f32_e32 v10, v26, v27
	ds_write_b128 v91, v[96:99] offset:47104
	v_pk_mul_f32 v[12:13], v[12:13], v[40:41]
	v_add_f32_dpp v0, v10, v10 quad_perm:[1,0,3,2] row_mask:0xf bank_mask:0xf bound_ctrl:1
	v_pk_fma_f32 v[60:61], v[6:7], v[16:17], v[12:13] op_sel_hi:[0,1,1]
	ds_read_b128 v[10:13], v90 offset:2560
	v_add_f32_dpp v0, v0, v0 quad_perm:[2,3,0,1] row_mask:0xf bank_mask:0xf bound_ctrl:1
	ds_read_b128 v[14:17], v89 offset:6656
	ds_read_b128 v[26:29], v90 offset:6656
	v_add_f32_dpp v0, v0, v0 row_half_mirror row_mask:0xf bank_mask:0xf bound_ctrl:1
	ds_read_b128 v[38:41], v90 offset:10752
	ds_read_b128 v[42:45], v89 offset:18944
	v_add_f32_dpp v0, v0, v0 row_ror:8 row_mask:0xf bank_mask:0xf bound_ctrl:1
	s_waitcnt lgkmcnt(12)
	v_pk_fma_f32 v[30:31], v[30:31], v[0:1], v[58:59] op_sel_hi:[1,0,1] neg_lo:[1,0,0] neg_hi:[1,0,0]
	v_pk_fma_f32 v[32:33], v[32:33], v[0:1], v[60:61] op_sel_hi:[1,0,1] neg_lo:[1,0,0] neg_hi:[1,0,0]
	s_waitcnt lgkmcnt(8)
	v_pk_mul_f32 v[34:35], v[34:35], v[30:31]
	v_pk_mul_f32 v[48:49], v[48:49], v[32:33]
	v_pk_mul_f32 v[18:19], v[18:19], v[30:31]
	v_pk_mul_f32 v[20:21], v[20:21], v[32:33]
	v_pk_fma_f32 v[30:31], v[46:47], v[30:31], v[48:49]
	v_pk_fma_f32 v[32:33], v[36:37], v[32:33], v[34:35]
	v_pk_fma_f32 v[58:59], v[6:7], v[22:23], v[18:19] op_sel:[1,0,0]
	v_add_f32_e32 v18, v32, v33
	v_add_f32_e32 v92, v30, v31
	v_pk_fma_f32 v[6:7], v[6:7], v[24:25], v[20:21] op_sel:[1,0,0]
	v_add_f32_dpp v0, v18, v18 quad_perm:[1,0,3,2] row_mask:0xf bank_mask:0xf bound_ctrl:1
	ds_read_b128 v[18:21], v90 offset:2816
	ds_read_b128 v[22:25], v89 offset:6912
	v_add_f32_dpp v0, v0, v0 quad_perm:[2,3,0,1] row_mask:0xf bank_mask:0xf bound_ctrl:1
	ds_read_b128 v[30:33], v90 offset:6912
	ds_read_b128 v[34:37], v90 offset:11008
	v_add_f32_dpp v0, v0, v0 row_half_mirror row_mask:0xf bank_mask:0xf bound_ctrl:1
	ds_read_b128 v[46:49], v89 offset:19200
	s_nop 0
	v_add_f32_dpp v0, v0, v0 row_ror:8 row_mask:0xf bank_mask:0xf bound_ctrl:1
	s_waitcnt lgkmcnt(12)
	v_pk_fma_f32 v[50:51], v[50:51], v[0:1], v[58:59] op_sel_hi:[1,0,1] neg_lo:[1,0,0] neg_hi:[1,0,0]
	v_pk_fma_f32 v[6:7], v[52:53], v[0:1], v[6:7] op_sel_hi:[1,0,1] neg_lo:[1,0,0] neg_hi:[1,0,0]
	s_waitcnt lgkmcnt(7)
	v_pk_mul_f32 v[26:27], v[26:27], v[50:51]
	v_pk_mul_f32 v[52:53], v[56:57], v[6:7]
	v_pk_mul_f32 v[10:11], v[10:11], v[50:51]
	v_pk_mul_f32 v[12:13], v[12:13], v[6:7]
	v_pk_fma_f32 v[50:51], v[54:55], v[50:51], v[52:53]
	v_pk_fma_f32 v[6:7], v[28:29], v[6:7], v[26:27]
	v_add_f32_e32 v6, v6, v7
	v_add_f32_e32 v93, v50, v51
	v_pk_fma_f32 v[54:55], v[8:9], v[14:15], v[10:11] op_sel_hi:[0,1,1]
	v_add_f32_dpp v0, v6, v6 quad_perm:[1,0,3,2] row_mask:0xf bank_mask:0xf bound_ctrl:1
	v_pk_fma_f32 v[56:57], v[8:9], v[16:17], v[12:13] op_sel_hi:[0,1,1]
	ds_read_b128 v[6:9], v90 offset:3072
	v_add_f32_dpp v0, v0, v0 quad_perm:[2,3,0,1] row_mask:0xf bank_mask:0xf bound_ctrl:1
	ds_read_b128 v[10:13], v89 offset:7168
	ds_read_b128 v[14:17], v90 offset:7168
	v_add_f32_dpp v0, v0, v0 row_half_mirror row_mask:0xf bank_mask:0xf bound_ctrl:1
	ds_read_b128 v[26:29], v90 offset:11264
	ds_read_b128 v[50:53], v89 offset:19456
	v_add_f32_dpp v0, v0, v0 row_ror:8 row_mask:0xf bank_mask:0xf bound_ctrl:1
	s_waitcnt lgkmcnt(11)
	v_pk_fma_f32 v[38:39], v[38:39], v[0:1], v[54:55] op_sel_hi:[1,0,1] neg_lo:[1,0,0] neg_hi:[1,0,0]
	v_pk_fma_f32 v[40:41], v[40:41], v[0:1], v[56:57] op_sel_hi:[1,0,1] neg_lo:[1,0,0] neg_hi:[1,0,0]
	s_waitcnt lgkmcnt(7)
	v_pk_mul_f32 v[30:31], v[30:31], v[38:39]
	v_pk_mul_f32 v[44:45], v[44:45], v[40:41]
	v_pk_mul_f32 v[18:19], v[18:19], v[38:39]
	v_pk_fma_f32 v[38:39], v[42:43], v[38:39], v[44:45]
	v_pk_fma_f32 v[30:31], v[32:33], v[40:41], v[30:31]
	v_pk_fma_f32 v[54:55], v[84:85], v[22:23], v[18:19] op_sel_hi:[0,1,1]
	v_add_f32_e32 v18, v30, v31
	v_add_f32_e32 v94, v38, v39
	v_pk_mul_f32 v[20:21], v[20:21], v[40:41]
	v_add_f32_dpp v0, v18, v18 quad_perm:[1,0,3,2] row_mask:0xf bank_mask:0xf bound_ctrl:1
	v_pk_fma_f32 v[56:57], v[84:85], v[24:25], v[20:21] op_sel_hi:[0,1,1]
	ds_read_b128 v[18:21], v90 offset:3328
	v_add_f32_dpp v0, v0, v0 quad_perm:[2,3,0,1] row_mask:0xf bank_mask:0xf bound_ctrl:1
	ds_read_b128 v[22:25], v89 offset:7424
	ds_read_b128 v[30:33], v90 offset:7424
	v_add_f32_dpp v0, v0, v0 row_half_mirror row_mask:0xf bank_mask:0xf bound_ctrl:1
	ds_read_b128 v[38:41], v90 offset:11520
	ds_read_b128 v[42:45], v89 offset:19712
	v_add_f32_dpp v0, v0, v0 row_ror:8 row_mask:0xf bank_mask:0xf bound_ctrl:1
	s_waitcnt lgkmcnt(11)
	v_pk_fma_f32 v[34:35], v[34:35], v[0:1], v[54:55] op_sel_hi:[1,0,1] neg_lo:[1,0,0] neg_hi:[1,0,0]
	v_pk_fma_f32 v[36:37], v[36:37], v[0:1], v[56:57] op_sel_hi:[1,0,1] neg_lo:[1,0,0] neg_hi:[1,0,0]
	s_waitcnt lgkmcnt(7)
	v_pk_mul_f32 v[14:15], v[14:15], v[34:35]
	v_pk_mul_f32 v[48:49], v[48:49], v[36:37]
	v_pk_mul_f32 v[6:7], v[6:7], v[34:35]
	v_pk_fma_f32 v[34:35], v[46:47], v[34:35], v[48:49]
	v_pk_fma_f32 v[14:15], v[16:17], v[36:37], v[14:15]
	v_pk_fma_f32 v[54:55], v[2:3], v[10:11], v[6:7] op_sel_hi:[0,1,1]
	v_add_f32_e32 v95, v34, v35
	v_add_f32_e32 v6, v14, v15
	ds_write_b128 v91, v[92:95] offset:51200
	v_pk_mul_f32 v[8:9], v[8:9], v[36:37]
	v_add_f32_dpp v0, v6, v6 quad_perm:[1,0,3,2] row_mask:0xf bank_mask:0xf bound_ctrl:1
	v_pk_fma_f32 v[56:57], v[2:3], v[12:13], v[8:9] op_sel_hi:[0,1,1]
	ds_read_b128 v[6:9], v90 offset:3584
	v_add_f32_dpp v0, v0, v0 quad_perm:[2,3,0,1] row_mask:0xf bank_mask:0xf bound_ctrl:1
	ds_read_b128 v[10:13], v89 offset:7680
	ds_read_b128 v[14:17], v90 offset:7680
	v_add_f32_dpp v0, v0, v0 row_half_mirror row_mask:0xf bank_mask:0xf bound_ctrl:1
	ds_read_b128 v[34:37], v90 offset:11776
	ds_read_b128 v[46:49], v89 offset:19968
	v_add_f32_dpp v0, v0, v0 row_ror:8 row_mask:0xf bank_mask:0xf bound_ctrl:1
	s_waitcnt lgkmcnt(12)
	v_pk_fma_f32 v[26:27], v[26:27], v[0:1], v[54:55] op_sel_hi:[1,0,1] neg_lo:[1,0,0] neg_hi:[1,0,0]
	v_pk_fma_f32 v[28:29], v[28:29], v[0:1], v[56:57] op_sel_hi:[1,0,1] neg_lo:[1,0,0] neg_hi:[1,0,0]
	s_waitcnt lgkmcnt(8)
	v_pk_mul_f32 v[30:31], v[30:31], v[26:27]
	v_pk_mul_f32 v[52:53], v[52:53], v[28:29]
	v_pk_mul_f32 v[18:19], v[18:19], v[26:27]
	v_pk_mul_f32 v[20:21], v[20:21], v[28:29]
	v_pk_fma_f32 v[26:27], v[50:51], v[26:27], v[52:53]
	v_pk_fma_f32 v[28:29], v[32:33], v[28:29], v[30:31]
	v_pk_fma_f32 v[54:55], v[2:3], v[22:23], v[18:19] op_sel:[1,0,0]
	v_add_f32_e32 v18, v28, v29
	v_add_f32_e32 v96, v26, v27
	v_pk_fma_f32 v[2:3], v[2:3], v[24:25], v[20:21] op_sel:[1,0,0]
	v_add_f32_dpp v0, v18, v18 quad_perm:[1,0,3,2] row_mask:0xf bank_mask:0xf bound_ctrl:1
	ds_read_b128 v[18:21], v90 offset:3840
	ds_read_b128 v[22:25], v89 offset:7936
	v_add_f32_dpp v0, v0, v0 quad_perm:[2,3,0,1] row_mask:0xf bank_mask:0xf bound_ctrl:1
	ds_read_b128 v[26:29], v90 offset:7936
	ds_read_b128 v[30:33], v90 offset:12032
	v_add_f32_dpp v0, v0, v0 row_half_mirror row_mask:0xf bank_mask:0xf bound_ctrl:1
	ds_read_b128 v[50:53], v89 offset:20224
	s_nop 0
	v_add_f32_dpp v0, v0, v0 row_ror:8 row_mask:0xf bank_mask:0xf bound_ctrl:1
	s_waitcnt lgkmcnt(12)
	v_pk_fma_f32 v[38:39], v[38:39], v[0:1], v[54:55] op_sel_hi:[1,0,1] neg_lo:[1,0,0] neg_hi:[1,0,0]
	v_pk_fma_f32 v[2:3], v[40:41], v[0:1], v[2:3] op_sel_hi:[1,0,1] neg_lo:[1,0,0] neg_hi:[1,0,0]
	s_waitcnt lgkmcnt(7)
	v_pk_mul_f32 v[14:15], v[14:15], v[38:39]
	v_pk_mul_f32 v[40:41], v[44:45], v[2:3]
	v_pk_mul_f32 v[8:9], v[8:9], v[2:3]
	v_pk_fma_f32 v[2:3], v[16:17], v[2:3], v[14:15]
	v_pk_mul_f32 v[6:7], v[6:7], v[38:39]
	v_add_f32_e32 v0, v2, v3
	v_pk_fma_f32 v[6:7], v[4:5], v[10:11], v[6:7] op_sel_hi:[0,1,1]
	v_pk_fma_f32 v[4:5], v[4:5], v[12:13], v[8:9] op_sel_hi:[0,1,1]
	v_add_f32_dpp v0, v0, v0 quad_perm:[1,0,3,2] row_mask:0xf bank_mask:0xf bound_ctrl:1
	v_pk_fma_f32 v[38:39], v[42:43], v[38:39], v[40:41]
	ds_read_b128 v[108:111], v88 offset:4096
	v_add_f32_dpp v0, v0, v0 quad_perm:[2,3,0,1] row_mask:0xf bank_mask:0xf bound_ctrl:1
	v_add_f32_e32 v97, v38, v39
	ds_read_b128 v[100:103], v88
	v_add_f32_dpp v0, v0, v0 row_half_mirror row_mask:0xf bank_mask:0xf bound_ctrl:1
	ds_read_b128 v[120:123], v88 offset:8192
	ds_read_b128 v[112:115], v88 offset:4352
	v_add_f32_dpp v0, v0, v0 row_ror:8 row_mask:0xf bank_mask:0xf bound_ctrl:1
	s_waitcnt lgkmcnt(10)
	v_pk_fma_f32 v[2:3], v[34:35], v[0:1], v[6:7] op_sel_hi:[1,0,1] neg_lo:[1,0,0] neg_hi:[1,0,0]
	v_pk_fma_f32 v[4:5], v[36:37], v[0:1], v[4:5] op_sel_hi:[1,0,1] neg_lo:[1,0,0] neg_hi:[1,0,0]
	s_waitcnt lgkmcnt(6)
	v_pk_mul_f32 v[8:9], v[26:27], v[2:3]
	v_pk_mul_f32 v[6:7], v[48:49], v[4:5]
	v_pk_mul_f32 v[10:11], v[18:19], v[2:3]
	v_pk_mul_f32 v[12:13], v[20:21], v[4:5]
	v_pk_fma_f32 v[2:3], v[46:47], v[2:3], v[6:7]
	v_pk_fma_f32 v[4:5], v[28:29], v[4:5], v[8:9]
	v_add_f32_e32 v98, v2, v3
	v_add_f32_e32 v2, v4, v5
	v_pk_fma_f32 v[8:9], v[86:87], v[24:25], v[12:13] op_sel_hi:[0,1,1]
	s_nop 0
	v_add_f32_dpp v0, v2, v2 quad_perm:[1,0,3,2] row_mask:0xf bank_mask:0xf bound_ctrl:1
	v_pk_fma_f32 v[6:7], v[86:87], v[22:23], v[10:11] op_sel_hi:[0,1,1]
	ds_read_b128 v[104:107], v88 offset:256
	v_add_f32_dpp v0, v0, v0 quad_perm:[2,3,0,1] row_mask:0xf bank_mask:0xf bound_ctrl:1
	ds_read_b128 v[128:131], v88 offset:8448
	ds_read_b128 v[124:127], v88 offset:4608
	v_add_f32_dpp v0, v0, v0 row_half_mirror row_mask:0xf bank_mask:0xf bound_ctrl:1
	ds_read_b128 v[116:119], v88 offset:512
	s_nop 0
	v_add_f32_dpp v0, v0, v0 row_ror:8 row_mask:0xf bank_mask:0xf bound_ctrl:1
	s_waitcnt lgkmcnt(9)
	v_pk_fma_f32 v[76:77], v[32:33], v[0:1], v[8:9] op_sel_hi:[1,0,1] neg_lo:[1,0,0] neg_hi:[1,0,0]
	v_pk_fma_f32 v[74:75], v[30:31], v[0:1], v[6:7] op_sel_hi:[1,0,1] neg_lo:[1,0,0] neg_hi:[1,0,0]
	s_waitcnt lgkmcnt(8)
	v_pk_mul_f32 v[2:3], v[52:53], v[76:77]
	s_nop 0
	v_pk_fma_f32 v[2:3], v[50:51], v[74:75], v[2:3]
	s_nop 0
	v_add_f32_e32 v99, v2, v3
	ds_write_b128 v91, v[96:99] offset:55296
	s_and_b32 s2, s26, 1
	s_mul_i32 s3, s2, 0x5400
	v_lshlrev_b32_e32 v91, 2, v87
	v_lshl_add_u32 v91, s2, 14, v91
	s_add_i32 s2, s3, 0
	v_add_u32_e32 v0, s2, v85
	v_add_u32_e32 v89, s2, v83
	v_add_u32_e32 v90, s96, v83
	s_add_i32 s96, s96, 0x3000
	s_cmp_eq_u32 s96, 0x1e800
	s_cselect_b32 s96, 0x20200, s96
	s_cmp_eq_u32 s96, 0x23200
	s_cselect_b32 s96, 0x12800, s96
	v_add_u32_e32 v88, s96, v83
	s_cmpk_eq_i32 s26, 0x110
	s_waitcnt lgkmcnt(0)
	s_barrier
	s_cbranch_scc0 .LBB0_1050
	s_setprio 0
